# adds: sample-mLSTM item prologue: the four tokens' q/k/gate loads issued up front (fresh registers for the reused destination/address pair), unpack and gate math after with counted waits
# speedup vs baseline: 1.0197x; 1.0046x over previous
.LBB0_425:
	s_and_b64 vcc, exec, s[0:1]
	s_cbranch_vccz .LBB0_442
	s_and_b32 s25, s70, 0x3fc
	s_and_b32 s71, s70, 3
	s_or_b32 s0, s25, s71
	v_mov_b32_e32 v89, v0
	s_mov_b64 s[80:81], s[74:75]
	s_add_u32 s4, s80, 0x1b36e000
	s_addc_u32 s5, s81, 0
	s_add_i32 s38, s0, 0xffffff80
	s_lshl_b64 s[86:87], s[38:39], 18
	v_readfirstlane_b32 s85, v89
	s_add_u32 s0, s58, s86
	v_and_b32_e32 v3, 63, v89
	s_addc_u32 s1, s59, s87
	s_ashr_i32 s6, s85, 1
	s_and_b32 s82, s6, 0xffffffe0
	s_waitcnt vmcnt(17)
	v_lshlrev_b32_e32 v36, 4, v3
	v_mov_b32_e32 v37, v2
	v_lshl_add_u64 v[68:69], s[0:1], 0, v[36:37]
	s_ashr_i32 s83, s82, 31
	s_or_b32 s0, s82, 1
	s_lshl_b64 s[88:89], s[82:83], 10
	s_ashr_i32 s1, s0, 31
	v_lshl_add_u64 v[4:5], v[68:69], 0, s[88:89]
	s_lshl_b64 s[0:1], s[0:1], 10
	global_load_dwordx4 v[32:35], v[4:5], off nt
	v_lshl_add_u64 v[4:5], v[68:69], 0, s[0:1]
	s_or_b32 s0, s82, 2
	s_ashr_i32 s1, s0, 31
	s_lshl_b64 s[0:1], s[0:1], 10
	global_load_dwordx4 v[28:31], v[4:5], off nt
	v_lshl_add_u64 v[4:5], v[68:69], 0, s[0:1]
	s_or_b32 s0, s82, 3
	s_ashr_i32 s1, s0, 31
	s_lshl_b64 s[0:1], s[0:1], 10
	global_load_dwordx4 v[24:27], v[4:5], off nt
	v_lshl_add_u64 v[4:5], v[68:69], 0, s[0:1]
	s_or_b32 s0, s82, 4
	s_ashr_i32 s1, s0, 31
	s_lshl_b64 s[0:1], s[0:1], 10
	global_load_dwordx4 v[20:23], v[4:5], off nt
	v_lshl_add_u64 v[4:5], v[68:69], 0, s[0:1]
	s_or_b32 s0, s82, 5
	s_ashr_i32 s1, s0, 31
	s_lshl_b64 s[0:1], s[0:1], 10
	global_load_dwordx4 v[16:19], v[4:5], off nt
	v_lshl_add_u64 v[4:5], v[68:69], 0, s[0:1]
	s_or_b32 s0, s82, 6
	s_ashr_i32 s1, s0, 31
	s_lshl_b64 s[0:1], s[0:1], 10
	global_load_dwordx4 v[12:15], v[4:5], off nt
	v_lshl_add_u64 v[4:5], v[68:69], 0, s[0:1]
	s_or_b32 s0, s82, 7
	s_ashr_i32 s1, s0, 31
	s_lshl_b64 s[0:1], s[0:1], 10
	s_add_i32 s91, s25, 0x3f80
	s_lshl_b32 s6, s71, 9
	s_add_u32 s7, s80, s6
	global_load_dwordx4 v[8:11], v[4:5], off nt
	v_lshl_add_u64 v[4:5], v[68:69], 0, s[0:1]
	s_addc_u32 s8, s81, 0
	s_lshl_b64 s[0:1], s[82:83], 1
	v_and_b32_e32 v37, 31, v89
	s_add_u32 s0, s7, s0
	s_addc_u32 s1, s8, s1
	v_lshlrev_b32_e32 v38, 1, v37
	v_mov_b32_e32 v39, v2
	v_lshl_add_u64 v[38:39], s[0:1], 0, v[38:39]
	s_mov_b64 s[0:1], 0xcc6e000
	s_lshl_b32 s84, s71, 2
	s_waitcnt vmcnt(7)
	v_lshl_add_u64 v[42:43], v[38:39], 0, s[0:1]
	s_add_u32 s0, s80, s84
	s_addc_u32 s1, s81, 0
	s_add_u32 s0, s0, 0x26a8000
	s_addc_u32 s1, s1, 0
	s_lshl_b32 s7, s91, 12
	s_add_u32 s7, s4, s7
	s_addc_u32 s9, s5, 0
	s_add_u32 s8, s7, s6
	s_addc_u32 s9, s9, 0
	v_lshlrev_b32_e32 v46, 3, v3
	global_load_dwordx4 v[4:7], v[4:5], off nt
	s_nop 0
	global_load_dwordx2 v[188:189], v46, s[8:9]
	global_load_dwordx2 v[194:195], v46, s[8:9] offset:2048
	s_lshl_b32 s8, s91, 11
	s_mov_b32 s9, s39
	s_lshl_b32 s7, s91, 5
	v_lshl_add_u64 v[196:197], v[42:43], 0, s[8:9]
	global_load_ushort v37, v[196:197], off
	v_mov_b32_e32 v204, s7
	s_add_i32 s7, s25, 0x3f81
	s_lshl_b32 s8, s7, 12
	s_add_u32 s8, s4, s8
	s_addc_u32 s9, s5, 0
	s_add_u32 s8, s8, s6
	s_addc_u32 s9, s9, 0
	global_load_dword v47, v204, s[0:1]
	global_load_dword v51, v204, s[0:1] offset:16
	s_nop 0
	global_load_dwordx2 v[190:191], v46, s[8:9]
	global_load_dwordx2 v[52:53], v46, s[8:9] offset:2048
	s_lshl_b32 s8, s7, 11
	s_mov_b32 s9, s39
	s_lshl_b32 s7, s7, 5
	v_lshl_add_u64 v[198:199], v[42:43], 0, s[8:9]
	global_load_ushort v44, v[198:199], off
	v_mov_b32_e32 v205, s7
	s_add_i32 s7, s25, 0x3f82
	s_lshl_b32 s8, s7, 12
	s_add_u32 s8, s4, s8
	s_addc_u32 s9, s5, 0
	s_add_u32 s8, s8, s6
	s_addc_u32 s9, s9, 0
	global_load_dword v50, v205, s[0:1]
	global_load_dword v56, v205, s[0:1] offset:16
	s_nop 0
	global_load_dwordx2 v[192:193], v46, s[8:9]
	global_load_dwordx2 v[40:41], v46, s[8:9] offset:2048
	s_lshl_b32 s8, s7, 11
	s_mov_b32 s9, s39
	s_lshl_b32 s7, s7, 5
	v_lshl_add_u64 v[200:201], v[42:43], 0, s[8:9]
	global_load_ushort v45, v[200:201], off
	v_mov_b32_e32 v206, s7
	s_add_i32 s7, s25, 0x3f83
	s_lshl_b32 s8, s7, 12
	s_add_u32 s4, s4, s8
	s_addc_u32 s5, s5, 0
	s_add_u32 s4, s4, s6
	s_addc_u32 s5, s5, 0
	global_load_dword v57, v206, s[0:1]
	global_load_dword v58, v206, s[0:1] offset:16
	global_load_dwordx2 v[54:55], v46, s[4:5]
	s_nop 0
	global_load_dwordx2 v[38:39], v46, s[4:5] offset:2048
	s_lshl_b32 s4, s7, 11
	s_mov_b32 s5, s39
	v_lshl_add_u64 v[42:43], v[42:43], 0, s[4:5]
	s_lshl_b32 s4, s7, 5
	global_load_ushort v42, v[42:43], off
	v_mov_b32_e32 v43, s4
	global_load_dword v49, v43, s[0:1]
	s_nop 0
	global_load_dword v43, v43, s[0:1] offset:16
	s_lshl_b64 s[0:1], s[38:39], 2
	s_add_u32 s0, s62, s0
	s_addc_u32 s1, s63, s1
	global_load_dword v207, v2, s[0:1]
	v_bfe_u32 v130, v89, 4, 2
	v_cmp_lt_i32_e32 vcc, v167, v161
	v_cmp_lt_u32_e64 s[10:11], 15, v3
	v_mov_b32_e32 v86, 0
	s_waitcnt vmcnt(20)
	v_lshlrev_b32_e32 v109, 16, v188
	v_and_b32_e32 v107, 0xffff0000, v188
	v_and_b32_e32 v71, 0xffff0000, v189
	v_lshlrev_b32_e32 v70, 16, v189
	s_waitcnt vmcnt(19)
	v_lshlrev_b32_e32 v80, 16, v195
	v_and_b32_e32 v81, 0xffff0000, v195
	v_lshlrev_b32_e32 v76, 16, v194
	v_and_b32_e32 v77, 0xffff0000, v194
	s_waitcnt vmcnt(15)
	v_lshlrev_b32_e32 v115, 16, v190
	v_and_b32_e32 v114, 0xffff0000, v190
	v_and_b32_e32 v73, 0xffff0000, v191
	v_lshlrev_b32_e32 v72, 16, v191
	s_waitcnt vmcnt(14)
	v_lshlrev_b32_e32 v78, 16, v52
	v_and_b32_e32 v79, 0xffff0000, v52
	v_lshlrev_b32_e32 v82, 16, v53
	v_and_b32_e32 v83, 0xffff0000, v53
	v_fma_f32 v60, v76, v115, 0
	v_fmac_f32_e32 v60, v77, v114
	v_fma_f32 v66, v78, v115, 0
	v_fmac_f32_e32 v66, v79, v114
	s_waitcnt vmcnt(10)
	v_lshlrev_b32_e32 v117, 16, v192
	v_and_b32_e32 v116, 0xffff0000, v192
	v_and_b32_e32 v75, 0xffff0000, v193
	v_lshlrev_b32_e32 v74, 16, v193
	v_cmp_eq_u32_e64 s[4:5], 1, v130
	v_fma_f32 v62, v76, v117, 0
	v_fmac_f32_e32 v62, v77, v116
	v_fma_f32 v87, v78, v117, 0
	v_fmac_f32_e32 v87, v79, v116
	v_cmp_eq_u32_e64 s[6:7], 2, v130
	v_cmp_eq_u32_e64 s[8:9], 3, v130
	s_waitcnt vmcnt(5)
	v_lshlrev_b32_e32 v119, 16, v54
	v_and_b32_e32 v118, 0xffff0000, v54
	v_and_b32_e32 v85, 0xffff0000, v55
	v_lshlrev_b32_e32 v84, 16, v55
	v_add_f32_e32 v55, v51, v56
	v_add_f32_e32 v56, v55, v58
	v_sub_f32_e32 v50, v50, v55
	s_waitcnt vmcnt(1)
	v_add_f32_e32 v46, v56, v43
	v_sub_f32_e32 v43, v47, v51
	v_sub_f32_e32 v48, v57, v56
	v_sub_f32_e32 v47, v49, v46
	v_max_f32_e32 v53, v43, v50
	v_add_f32_e32 v49, v51, v43
	v_max_f32_e32 v57, v53, v48
	v_add_f32_e32 v53, v55, v53
	v_max_f32_e32 v58, v57, v47
	v_add_f32_e32 v57, v56, v57
	v_fma_f32 v64, v76, v119, 0
	v_fmac_f32_e32 v64, v77, v118
	v_fma_f32 v88, v78, v119, 0
	v_fmac_f32_e32 v88, v79, v118
	v_pk_mul_f32 v[90:91], v[82:83], v[84:85]
	s_waitcnt vmcnt(0)
	v_add_f32_e32 v52, v51, v207
	v_max_f32_e32 v121, v52, v49
	v_add_f32_e32 v49, v55, v207
	v_max_f32_e32 v122, v49, v53
	v_add_f32_e32 v53, v56, v207
	v_max_f32_e32 v123, v53, v57
	v_sub_f32_e32 v51, v51, v121
	v_sub_f32_e32 v55, v55, v122
	v_cndmask_b32_e64 v51, v51, v55, s[4:5]
	v_sub_f32_e32 v55, v56, v123
	v_cndmask_b32_e32 v56, v160, v167, vcc
	v_cmp_lt_i32_e32 vcc, v166, v161
	v_lshlrev_b32_e32 v124, 2, v56
	v_add_f32_e32 v54, v207, v46
	v_cndmask_b32_e32 v56, v160, v166, vcc
	v_cmp_lt_i32_e32 vcc, v165, v161
	v_lshlrev_b32_e32 v125, 2, v56
	v_add_f32_e32 v57, v46, v58
	v_cndmask_b32_e32 v56, v160, v165, vcc
	v_cmp_lt_i32_e32 vcc, v164, v161
	v_lshlrev_b32_e32 v126, 2, v56
	v_fma_f32 v58, v76, v109, 0
	v_cndmask_b32_e32 v56, v160, v164, vcc
	v_cmp_lt_i32_e32 vcc, v163, v161
	v_lshlrev_b32_e32 v127, 2, v56
	v_max_f32_e32 v120, v54, v57
	v_cndmask_b32_e32 v56, v160, v163, vcc
	v_cmp_lt_i32_e32 vcc, v162, v161
	v_lshlrev_b32_e32 v128, 2, v56
	v_fmac_f32_e32 v58, v77, v107
	v_cndmask_b32_e32 v56, v160, v162, vcc
	v_lshlrev_b32_e32 v129, 2, v56
	v_pk_mul_f32 v[56:57], v[70:71], v[80:81]
	v_cndmask_b32_e64 v51, v51, v55, s[6:7]
	v_add_f32_e32 v56, v56, v58
	v_pk_mul_f32 v[58:59], v[80:81], v[72:73]
	v_add_f32_e32 v56, v57, v56
	v_add_f32_e32 v58, v58, v60
	v_pk_mul_f32 v[60:61], v[80:81], v[74:75]
	v_add_f32_e32 v58, v59, v58
	v_add_f32_e32 v60, v60, v62
	v_pk_mul_f32 v[62:63], v[80:81], v[84:85]
	v_add_f32_e32 v60, v61, v60
	v_add_f32_e32 v62, v62, v64
	v_pk_mul_f32 v[64:65], v[72:73], v[82:83]
	v_add_f32_e32 v62, v63, v62
	v_add_f32_e32 v64, v64, v66
	v_pk_mul_f32 v[66:67], v[82:83], v[74:75]
	v_add_f32_e32 v64, v65, v64
	v_add_f32_e32 v66, v66, v87
	v_add_f32_e32 v87, v90, v88
	v_add_f32_e32 v66, v67, v66
	v_add_f32_e32 v87, v91, v87
	ds_bpermute_b32 v57, v124, v56
	ds_bpermute_b32 v59, v124, v58
	ds_bpermute_b32 v61, v124, v60
	ds_bpermute_b32 v63, v124, v62
	ds_bpermute_b32 v65, v124, v64
	ds_bpermute_b32 v67, v124, v66
	ds_bpermute_b32 v88, v124, v87
	s_waitcnt lgkmcnt(6)
	v_add_f32_e32 v56, v56, v57
	s_waitcnt lgkmcnt(5)
	v_add_f32_e32 v58, v58, v59
	s_waitcnt lgkmcnt(4)
	v_add_f32_e32 v60, v60, v61
	s_waitcnt lgkmcnt(3)
	v_add_f32_e32 v62, v62, v63
	s_waitcnt lgkmcnt(2)
	v_add_f32_e32 v64, v64, v65
	s_waitcnt lgkmcnt(1)
	v_add_f32_e32 v66, v66, v67
	s_waitcnt lgkmcnt(0)
	v_add_f32_e32 v87, v87, v88
	ds_bpermute_b32 v57, v125, v56
	ds_bpermute_b32 v59, v125, v58
	ds_bpermute_b32 v61, v125, v60
	ds_bpermute_b32 v63, v125, v62
	ds_bpermute_b32 v65, v125, v64
	ds_bpermute_b32 v67, v125, v66
	ds_bpermute_b32 v88, v125, v87
	s_waitcnt lgkmcnt(6)
	v_add_f32_e32 v56, v56, v57
	s_waitcnt lgkmcnt(5)
	v_add_f32_e32 v58, v58, v59
	s_waitcnt lgkmcnt(4)
	v_add_f32_e32 v60, v60, v61
	s_waitcnt lgkmcnt(3)
	v_add_f32_e32 v62, v62, v63
	s_waitcnt lgkmcnt(2)
	v_add_f32_e32 v64, v64, v65
	s_waitcnt lgkmcnt(1)
	v_add_f32_e32 v66, v66, v67
	s_waitcnt lgkmcnt(0)
	v_add_f32_e32 v87, v87, v88
	ds_bpermute_b32 v57, v126, v56
	ds_bpermute_b32 v59, v126, v58
	ds_bpermute_b32 v61, v126, v60
	ds_bpermute_b32 v63, v126, v62
	ds_bpermute_b32 v65, v126, v64
	ds_bpermute_b32 v67, v126, v66
	ds_bpermute_b32 v88, v126, v87
	s_waitcnt lgkmcnt(6)
	v_add_f32_e32 v56, v56, v57
	s_waitcnt lgkmcnt(5)
	v_add_f32_e32 v58, v58, v59
	s_waitcnt lgkmcnt(4)
	v_add_f32_e32 v60, v60, v61
	s_waitcnt lgkmcnt(3)
	v_add_f32_e32 v62, v62, v63
	s_waitcnt lgkmcnt(2)
	v_add_f32_e32 v64, v64, v65
	s_waitcnt lgkmcnt(1)
	v_add_f32_e32 v66, v66, v67
	s_waitcnt lgkmcnt(0)
	v_add_f32_e32 v87, v87, v88
	ds_bpermute_b32 v57, v127, v56
	ds_bpermute_b32 v59, v127, v58
	ds_bpermute_b32 v61, v127, v60
	ds_bpermute_b32 v63, v127, v62
	ds_bpermute_b32 v65, v127, v64
	ds_bpermute_b32 v67, v127, v66
	ds_bpermute_b32 v88, v127, v87
	s_waitcnt lgkmcnt(6)
	v_add_f32_e32 v56, v56, v57
	s_waitcnt lgkmcnt(5)
	v_add_f32_e32 v58, v58, v59
	s_waitcnt lgkmcnt(4)
	v_add_f32_e32 v60, v60, v61
	s_waitcnt lgkmcnt(3)
	v_add_f32_e32 v62, v62, v63
	s_waitcnt lgkmcnt(2)
	v_add_f32_e32 v64, v64, v65
	s_waitcnt lgkmcnt(1)
	v_add_f32_e32 v66, v66, v67
	s_waitcnt lgkmcnt(0)
	v_add_f32_e32 v87, v87, v88
	ds_bpermute_b32 v57, v128, v56
	ds_bpermute_b32 v59, v128, v58
	ds_bpermute_b32 v61, v128, v60
	ds_bpermute_b32 v63, v128, v62
	ds_bpermute_b32 v65, v128, v64
	ds_bpermute_b32 v67, v128, v66
	ds_bpermute_b32 v88, v128, v87
	s_waitcnt lgkmcnt(6)
	v_add_f32_e32 v56, v56, v57
	s_waitcnt lgkmcnt(5)
	v_add_f32_e32 v58, v58, v59
	s_waitcnt lgkmcnt(4)
	v_add_f32_e32 v60, v60, v61
	s_waitcnt lgkmcnt(3)
	v_add_f32_e32 v62, v62, v63
	s_waitcnt lgkmcnt(2)
	v_add_f32_e32 v64, v64, v65
	s_waitcnt lgkmcnt(1)
	v_add_f32_e32 v66, v66, v67
	s_waitcnt lgkmcnt(0)
	v_add_f32_e32 v87, v87, v88
	ds_bpermute_b32 v57, v129, v56
	ds_bpermute_b32 v59, v129, v58
	ds_bpermute_b32 v61, v129, v60
	ds_bpermute_b32 v63, v129, v62
	ds_bpermute_b32 v65, v129, v64
	ds_bpermute_b32 v67, v129, v66
	ds_bpermute_b32 v90, v129, v87
	v_sub_f32_e32 v55, v46, v120
	v_cndmask_b32_e64 v51, v51, v55, s[8:9]
	v_cmp_gt_u32_e32 vcc, 16, v3
	v_mov_b32_e32 v88, 0
	s_and_saveexec_b64 s[0:1], s[10:11]
	s_cbranch_execz .LBB0_428
	s_waitcnt lgkmcnt(2)
	v_add_f32_e32 v64, v64, v65
	s_waitcnt lgkmcnt(1)
	v_add_f32_e32 v65, v66, v67
	v_add_f32_e32 v66, v50, v51
	v_mul_f32_e32 v66, 0x3fb8aa3b, v66
	v_exp_f32_e32 v66, v66
	s_waitcnt lgkmcnt(0)
	v_add_f32_e32 v67, v87, v90
	v_cndmask_b32_e64 v65, v67, v65, s[6:7]
	v_cndmask_b32_e64 v64, v65, v64, s[4:5]
	v_mul_f32_e32 v88, v66, v64
